# attention phases: one static priority raise for waves 4-7 around the unit loop
# speedup vs baseline: 1.0018x; 1.0018x over previous
.Lattn_prio_on:
	v_readfirstlane_b32 s6, v234
	s_nop 3
	s_cmpk_gt_u32 s6, 0xff
	s_cbranch_scc0 .LBB0_164
	s_setprio 1
	s_branch .LBB0_164
.Lattn_prio_off:
	s_setprio 0
	s_branch .LBB0_235
